# RG-LRU conv staging: second half's 4 loads issued before the first half's wait (second register set)
# baseline (speedup 1.0000x reference)
.LBB0_296:
	s_mul_i32 s2, s28, s70
	s_add_i32 s2, s2, s27
	s_bfe_u32 s37, s2, 0x60003
	s_mov_b64 s[8:9], s[74:75]
	s_waitcnt lgkmcnt(0)
	s_barrier
	s_lshl_b32 s35, s37, 6
	v_lshlrev_b32_e32 v144, 1, v151
	s_add_i32 s3, s35, -2
	v_lshl_add_u64 v[8:9], s[8:9], 0, v[144:145]
	s_mov_b64 s[8:9], 0x91e0000
	s_ashr_i32 s2, s2, 9
	v_lshl_add_u64 v[48:49], v[8:9], 0, s[8:9]
	v_add_u32_e32 v50, s3, v154
	s_waitcnt vmcnt(0)
	v_mov_b64_e32 v[14:15], v[6:7]
	s_lshl_b32 s36, s2, 12
	v_cmp_gt_u32_e64 s[8:9], s67, v50
	v_mov_b64_e32 v[12:13], v[4:5]
	v_mov_b64_e32 v[10:11], v[2:3]
	v_mov_b64_e32 v[8:9], v[0:1]
	v_mov_b64_e32 v[216:217], 0
	v_mov_b64_e32 v[218:219], 0
	s_and_saveexec_b64 s[12:13], s[8:9]
	v_or_b32_e32 v232, s36, v50
	v_ashrrev_i32_e32 v233, 31, v232
	v_lshlrev_b64 v[232:233], 10, v[232:233]
	v_lshl_add_u64 v[232:233], v[48:49], 0, v[232:233]
	global_load_dwordx4 v[216:219], v[232:233], off
	s_or_b64 exec, exec, s[12:13]
	v_add_u32_e32 v51, 1, v50
	v_cmp_gt_u32_e64 s[8:9], s67, v51
	v_mov_b64_e32 v[220:221], 0
	v_mov_b64_e32 v[222:223], 0
	s_and_saveexec_b64 s[12:13], s[8:9]
	v_or_b32_e32 v234, s36, v51
	v_ashrrev_i32_e32 v235, 31, v234
	v_lshlrev_b64 v[234:235], 10, v[234:235]
	v_lshl_add_u64 v[234:235], v[48:49], 0, v[234:235]
	global_load_dwordx4 v[220:223], v[234:235], off
	s_or_b64 exec, exec, s[12:13]
	v_add_u32_e32 v51, s35, v154
	v_cmp_gt_u32_e64 s[8:9], s67, v51
	v_mov_b64_e32 v[224:225], 0
	v_mov_b64_e32 v[226:227], 0
	s_and_saveexec_b64 s[12:13], s[8:9]
	v_or_b32_e32 v236, s36, v51
	v_ashrrev_i32_e32 v237, 31, v236
	v_lshlrev_b64 v[236:237], 10, v[236:237]
	v_lshl_add_u64 v[236:237], v[48:49], 0, v[236:237]
	global_load_dwordx4 v[224:227], v[236:237], off
	s_or_b64 exec, exec, s[12:13]
	v_add_u32_e32 v50, 3, v50
	v_cmp_gt_u32_e64 s[8:9], s67, v50
	v_mov_b64_e32 v[228:229], 0
	v_mov_b64_e32 v[230:231], 0
	s_and_saveexec_b64 s[12:13], s[8:9]
	v_or_b32_e32 v238, s36, v50
	v_ashrrev_i32_e32 v239, 31, v238
	v_lshlrev_b64 v[238:239], 10, v[238:239]
	v_lshl_add_u64 v[238:239], v[48:49], 0, v[238:239]
	global_load_dwordx4 v[228:231], v[238:239], off
	s_or_b64 exec, exec, s[12:13]
	v_add_u32_e32 v50, s3, v157
	v_cmp_gt_u32_e64 s[8:9], s67, v50
	v_mov_b64_e32 v[164:165], 0
	v_mov_b64_e32 v[166:167], 0
	s_and_saveexec_b64 s[12:13], s[8:9]
	v_or_b32_e32 v232, s36, v50
	v_ashrrev_i32_e32 v233, 31, v232
	v_lshlrev_b64 v[232:233], 10, v[232:233]
	v_lshl_add_u64 v[232:233], v[48:49], 0, v[232:233]
	global_load_dwordx4 v[164:167], v[232:233], off
	s_or_b64 exec, exec, s[12:13]
	v_add_u32_e32 v51, 1, v50
	v_cmp_gt_u32_e64 s[8:9], s67, v51
	v_mov_b64_e32 v[168:169], 0
	v_mov_b64_e32 v[170:171], 0
	s_and_saveexec_b64 s[12:13], s[8:9]
	v_or_b32_e32 v234, s36, v51
	v_ashrrev_i32_e32 v235, 31, v234
	v_lshlrev_b64 v[234:235], 10, v[234:235]
	v_lshl_add_u64 v[234:235], v[48:49], 0, v[234:235]
	global_load_dwordx4 v[168:171], v[234:235], off
	s_or_b64 exec, exec, s[12:13]
	v_add_u32_e32 v51, s35, v157
	v_cmp_gt_u32_e64 s[8:9], s67, v51
	v_mov_b64_e32 v[172:173], 0
	v_mov_b64_e32 v[174:175], 0
	s_and_saveexec_b64 s[12:13], s[8:9]
	v_or_b32_e32 v236, s36, v51
	v_ashrrev_i32_e32 v237, 31, v236
	v_lshlrev_b64 v[236:237], 10, v[236:237]
	v_lshl_add_u64 v[236:237], v[48:49], 0, v[236:237]
	global_load_dwordx4 v[172:175], v[236:237], off
	s_or_b64 exec, exec, s[12:13]
	v_add_u32_e32 v50, 3, v50
	v_cmp_gt_u32_e64 s[8:9], s67, v50
	v_mov_b64_e32 v[176:177], 0
	v_mov_b64_e32 v[178:179], 0
	s_and_saveexec_b64 s[12:13], s[8:9]
	v_or_b32_e32 v238, s36, v50
	v_ashrrev_i32_e32 v239, 31, v238
	v_lshlrev_b64 v[238:239], 10, v[238:239]
	v_lshl_add_u64 v[238:239], v[48:49], 0, v[238:239]
	global_load_dwordx4 v[176:179], v[238:239], off
	s_or_b64 exec, exec, s[12:13]
	s_waitcnt vmcnt(4)
	v_lshlrev_b32_e32 v52, 16, v216
	v_and_b32_e32 v53, 0xffff0000, v216
	v_lshlrev_b32_e32 v8, 16, v217
	v_and_b32_e32 v9, 0xffff0000, v217
	v_lshlrev_b32_e32 v12, 16, v218
	v_and_b32_e32 v13, 0xffff0000, v218
	v_lshlrev_b32_e32 v10, 16, v219
	v_and_b32_e32 v11, 0xffff0000, v219
	v_pk_fma_f32 v[14:15], v[22:23], v[10:11], v[6:7]
	v_pk_fma_f32 v[12:13], v[20:21], v[12:13], v[4:5]
	v_pk_fma_f32 v[10:11], v[18:19], v[8:9], v[2:3]
	v_pk_fma_f32 v[8:9], v[16:17], v[52:53], v[0:1]
	v_lshlrev_b32_e32 v56, 16, v220
	v_and_b32_e32 v57, 0xffff0000, v220
	v_lshlrev_b32_e32 v52, 16, v221
	v_and_b32_e32 v53, 0xffff0000, v221
	v_lshlrev_b32_e32 v58, 16, v222
	v_and_b32_e32 v59, 0xffff0000, v222
	v_lshlrev_b32_e32 v54, 16, v223
	v_and_b32_e32 v55, 0xffff0000, v223
	v_pk_fma_f32 v[14:15], v[30:31], v[54:55], v[14:15]
	v_pk_fma_f32 v[12:13], v[28:29], v[58:59], v[12:13]
	v_pk_fma_f32 v[10:11], v[26:27], v[52:53], v[10:11]
	v_pk_fma_f32 v[8:9], v[24:25], v[56:57], v[8:9]
	v_lshlrev_b32_e32 v56, 16, v224
	v_and_b32_e32 v57, 0xffff0000, v224
	v_lshlrev_b32_e32 v52, 16, v225
	v_and_b32_e32 v53, 0xffff0000, v225
	v_lshlrev_b32_e32 v58, 16, v226
	v_and_b32_e32 v59, 0xffff0000, v226
	v_lshlrev_b32_e32 v54, 16, v227
	v_and_b32_e32 v55, 0xffff0000, v227
	v_pk_fma_f32 v[14:15], v[38:39], v[54:55], v[14:15]
	v_pk_fma_f32 v[12:13], v[36:37], v[58:59], v[12:13]
	v_pk_fma_f32 v[10:11], v[34:35], v[52:53], v[10:11]
	v_pk_fma_f32 v[8:9], v[32:33], v[56:57], v[8:9]
	v_lshlrev_b32_e32 v54, 16, v228
	v_and_b32_e32 v55, 0xffff0000, v228
	v_lshlrev_b32_e32 v50, 16, v229
	v_and_b32_e32 v51, 0xffff0000, v229
	v_lshlrev_b32_e32 v56, 16, v230
	v_and_b32_e32 v57, 0xffff0000, v230
	v_lshlrev_b32_e32 v52, 16, v231
	v_and_b32_e32 v53, 0xffff0000, v231
	v_pk_fma_f32 v[14:15], v[46:47], v[52:53], v[14:15]
	v_pk_fma_f32 v[12:13], v[44:45], v[56:57], v[12:13]
	v_pk_fma_f32 v[10:11], v[42:43], v[50:51], v[10:11]
	v_pk_fma_f32 v[8:9], v[40:41], v[54:55], v[8:9]
	v_cvt_pk_bf16_f32 v8, v8, v9
	v_cvt_pk_bf16_f32 v9, v10, v11
	v_cvt_pk_bf16_f32 v10, v12, v13
	v_cvt_pk_bf16_f32 v11, v14, v15
	ds_write_b128 v159, v[8:11]
	v_mov_b64_e32 v[14:15], v[6:7]
	v_mov_b64_e32 v[12:13], v[4:5]
	v_mov_b64_e32 v[10:11], v[2:3]
	v_mov_b64_e32 v[8:9], v[0:1]
	s_waitcnt vmcnt(0)
	v_lshlrev_b32_e32 v52, 16, v164
	v_and_b32_e32 v53, 0xffff0000, v164
	v_lshlrev_b32_e32 v8, 16, v165
	v_and_b32_e32 v9, 0xffff0000, v165
	v_lshlrev_b32_e32 v12, 16, v166
	v_and_b32_e32 v13, 0xffff0000, v166
	v_lshlrev_b32_e32 v10, 16, v167
	v_and_b32_e32 v11, 0xffff0000, v167
	v_pk_fma_f32 v[14:15], v[22:23], v[10:11], v[6:7]
	v_pk_fma_f32 v[12:13], v[20:21], v[12:13], v[4:5]
	v_pk_fma_f32 v[10:11], v[18:19], v[8:9], v[2:3]
	v_pk_fma_f32 v[8:9], v[16:17], v[52:53], v[0:1]
	v_lshlrev_b32_e32 v56, 16, v168
	v_and_b32_e32 v57, 0xffff0000, v168
	v_lshlrev_b32_e32 v52, 16, v169
	v_and_b32_e32 v53, 0xffff0000, v169
	v_lshlrev_b32_e32 v58, 16, v170
	v_and_b32_e32 v59, 0xffff0000, v170
	v_lshlrev_b32_e32 v54, 16, v171
	v_and_b32_e32 v55, 0xffff0000, v171
	v_pk_fma_f32 v[14:15], v[30:31], v[54:55], v[14:15]
	v_pk_fma_f32 v[12:13], v[28:29], v[58:59], v[12:13]
	v_pk_fma_f32 v[10:11], v[26:27], v[52:53], v[10:11]
	v_pk_fma_f32 v[8:9], v[24:25], v[56:57], v[8:9]
	v_lshlrev_b32_e32 v56, 16, v172
	v_and_b32_e32 v57, 0xffff0000, v172
	v_lshlrev_b32_e32 v52, 16, v173
	v_and_b32_e32 v53, 0xffff0000, v173
	v_lshlrev_b32_e32 v58, 16, v174
	v_and_b32_e32 v59, 0xffff0000, v174
	v_lshlrev_b32_e32 v54, 16, v175
	v_and_b32_e32 v55, 0xffff0000, v175
	v_pk_fma_f32 v[14:15], v[38:39], v[54:55], v[14:15]
	v_pk_fma_f32 v[12:13], v[36:37], v[58:59], v[12:13]
	v_pk_fma_f32 v[10:11], v[34:35], v[52:53], v[10:11]
	v_pk_fma_f32 v[8:9], v[32:33], v[56:57], v[8:9]
	v_lshlrev_b32_e32 v52, 16, v176
	v_and_b32_e32 v53, 0xffff0000, v176
	v_lshlrev_b32_e32 v48, 16, v177
	v_and_b32_e32 v49, 0xffff0000, v177
	v_lshlrev_b32_e32 v54, 16, v178
	v_and_b32_e32 v55, 0xffff0000, v178
	v_lshlrev_b32_e32 v50, 16, v179
	v_and_b32_e32 v51, 0xffff0000, v179
	v_pk_fma_f32 v[14:15], v[46:47], v[50:51], v[14:15]
	v_pk_fma_f32 v[12:13], v[44:45], v[54:55], v[12:13]
	v_pk_fma_f32 v[10:11], v[42:43], v[48:49], v[10:11]
	v_pk_fma_f32 v[8:9], v[40:41], v[52:53], v[8:9]
	s_mov_b64 s[8:9], s[74:75]
	v_cvt_pk_bf16_f32 v8, v8, v9
	v_cvt_pk_bf16_f32 v9, v10, v11
	v_cvt_pk_bf16_f32 v10, v12, v13
	v_cvt_pk_bf16_f32 v11, v14, v15
	ds_write_b128 v160, v[8:11]
	s_lshl_b32 s3, s26, 3
	s_add_u32 s8, s8, s3
	s_addc_u32 s9, s9, 0
	v_mov_b32_e32 v141, v145
	v_lshl_add_u64 v[8:9], s[8:9], 0, v[140:141]
	s_mov_b64 s[8:9], 0x115e0000
	v_lshl_add_u64 v[8:9], v[8:9], 0, s[8:9]
	s_lshl_b32 s12, s2, 1
	v_add_u32_e32 v12, v156, v155
	v_cmp_ne_u32_e64 s[8:9], s37, v76
	s_and_saveexec_b64 s[2:3], s[8:9]
	v_cmp_le_i32_e64 s[8:9], s37, v76
	s_nop 1
	v_cndmask_b32_e64 v10, 0, 1, s[8:9]
	v_or_b32_e32 v10, s12, v10
	v_ashrrev_i32_e32 v11, 31, v10
	v_lshlrev_b64 v[10:11], 18, v[10:11]
	v_lshl_add_u64 v[10:11], v[8:9], 0, v[10:11]
	v_lshl_add_u64 v[10:11], v[10:11], 0, v[78:79]
	global_load_dwordx2 v[216:217], v[10:11], off
	s_or_b64 exec, exec, s[2:3]
	v_cmp_ne_u32_e64 s[8:9], s37, v84
	s_and_saveexec_b64 s[2:3], s[8:9]
	v_cmp_le_i32_e64 s[8:9], s37, v84
	s_nop 1
	v_cndmask_b32_e64 v10, 0, 1, s[8:9]
	v_or_b32_e32 v10, s12, v10
	v_ashrrev_i32_e32 v11, 31, v10
	v_lshlrev_b64 v[10:11], 18, v[10:11]
	v_lshl_add_u64 v[10:11], v[8:9], 0, v[10:11]
	v_lshl_add_u64 v[10:11], v[10:11], 0, v[86:87]
	global_load_dwordx2 v[218:219], v[10:11], off
	s_or_b64 exec, exec, s[2:3]
	v_cmp_ne_u32_e64 s[8:9], s37, v92
	s_and_saveexec_b64 s[2:3], s[8:9]
	v_cmp_le_i32_e64 s[8:9], s37, v92
	s_nop 1
	v_cndmask_b32_e64 v10, 0, 1, s[8:9]
	v_or_b32_e32 v10, s12, v10
	v_ashrrev_i32_e32 v11, 31, v10
	v_lshlrev_b64 v[10:11], 18, v[10:11]
	v_lshl_add_u64 v[10:11], v[8:9], 0, v[10:11]
	v_lshl_add_u64 v[10:11], v[10:11], 0, v[94:95]
	global_load_dwordx2 v[220:221], v[10:11], off
	s_or_b64 exec, exec, s[2:3]
	v_cmp_ne_u32_e64 s[8:9], s37, v100
	s_and_saveexec_b64 s[2:3], s[8:9]
	v_cmp_le_i32_e64 s[8:9], s37, v100
	s_nop 1
	v_cndmask_b32_e64 v10, 0, 1, s[8:9]
	v_or_b32_e32 v10, s12, v10
	v_ashrrev_i32_e32 v11, 31, v10
	v_lshlrev_b64 v[10:11], 18, v[10:11]
	v_lshl_add_u64 v[10:11], v[8:9], 0, v[10:11]
	v_lshl_add_u64 v[10:11], v[10:11], 0, v[102:103]
	global_load_dwordx2 v[222:223], v[10:11], off
	s_or_b64 exec, exec, s[2:3]
	v_cmp_ne_u32_e64 s[8:9], s37, v108
	s_and_saveexec_b64 s[2:3], s[8:9]
	v_cmp_le_i32_e64 s[8:9], s37, v108
	s_nop 1
	v_cndmask_b32_e64 v10, 0, 1, s[8:9]
	v_or_b32_e32 v10, s12, v10
	v_ashrrev_i32_e32 v11, 31, v10
	v_lshlrev_b64 v[10:11], 18, v[10:11]
	v_lshl_add_u64 v[10:11], v[8:9], 0, v[10:11]
	v_lshl_add_u64 v[10:11], v[10:11], 0, v[110:111]
	global_load_dwordx2 v[224:225], v[10:11], off
	s_or_b64 exec, exec, s[2:3]
	v_cmp_ne_u32_e64 s[8:9], s37, v116
	s_and_saveexec_b64 s[2:3], s[8:9]
	v_cmp_le_i32_e64 s[8:9], s37, v116
	s_nop 1
	v_cndmask_b32_e64 v10, 0, 1, s[8:9]
	v_or_b32_e32 v10, s12, v10
	v_ashrrev_i32_e32 v11, 31, v10
	v_lshlrev_b64 v[10:11], 18, v[10:11]
	v_lshl_add_u64 v[10:11], v[8:9], 0, v[10:11]
	v_lshl_add_u64 v[10:11], v[10:11], 0, v[118:119]
	global_load_dwordx2 v[226:227], v[10:11], off
	s_or_b64 exec, exec, s[2:3]
	v_cmp_ne_u32_e64 s[8:9], s37, v124
	s_and_saveexec_b64 s[2:3], s[8:9]
	v_cmp_le_i32_e64 s[8:9], s37, v124
	s_nop 1
	v_cndmask_b32_e64 v10, 0, 1, s[8:9]
	v_or_b32_e32 v10, s12, v10
	v_ashrrev_i32_e32 v11, 31, v10
	v_lshlrev_b64 v[10:11], 18, v[10:11]
	v_lshl_add_u64 v[10:11], v[8:9], 0, v[10:11]
	v_lshl_add_u64 v[10:11], v[10:11], 0, v[126:127]
	global_load_dwordx2 v[228:229], v[10:11], off
	s_or_b64 exec, exec, s[2:3]
	v_cmp_ne_u32_e64 s[8:9], s37, v132
	s_and_saveexec_b64 s[2:3], s[8:9]
	v_cmp_le_i32_e64 s[8:9], s37, v132
	s_nop 1
	v_cndmask_b32_e64 v10, 0, 1, s[8:9]
	v_or_b32_e32 v10, s12, v10
	v_ashrrev_i32_e32 v11, 31, v10
	v_lshlrev_b64 v[10:11], 18, v[10:11]
	v_lshl_add_u64 v[10:11], v[8:9], 0, v[10:11]
	v_lshl_add_u64 v[10:11], v[10:11], 0, v[134:135]
	global_load_dwordx2 v[230:231], v[10:11], off
	s_or_b64 exec, exec, s[2:3]
	v_cmp_ne_u32_e64 s[8:9], s37, v80
	s_and_saveexec_b64 s[2:3], s[8:9]
	v_cmp_le_i32_e64 s[8:9], s37, v80
	s_nop 1
	v_cndmask_b32_e64 v10, 0, 1, s[8:9]
	v_or_b32_e32 v10, s12, v10
	v_ashrrev_i32_e32 v11, 31, v10
	v_lshlrev_b64 v[10:11], 18, v[10:11]
	v_lshl_add_u64 v[10:11], v[8:9], 0, v[10:11]
	v_lshl_add_u64 v[10:11], v[10:11], 0, v[82:83]
	global_load_dwordx2 v[232:233], v[10:11], off
	s_or_b64 exec, exec, s[2:3]
	v_cmp_ne_u32_e64 s[8:9], s37, v88
	s_and_saveexec_b64 s[2:3], s[8:9]
	v_cmp_le_i32_e64 s[8:9], s37, v88
	s_nop 1
	v_cndmask_b32_e64 v10, 0, 1, s[8:9]
	v_or_b32_e32 v10, s12, v10
	v_ashrrev_i32_e32 v11, 31, v10
	v_lshlrev_b64 v[10:11], 18, v[10:11]
	v_lshl_add_u64 v[10:11], v[8:9], 0, v[10:11]
	v_lshl_add_u64 v[10:11], v[10:11], 0, v[90:91]
	global_load_dwordx2 v[234:235], v[10:11], off
	s_or_b64 exec, exec, s[2:3]
	v_cmp_ne_u32_e64 s[8:9], s37, v96
	s_and_saveexec_b64 s[2:3], s[8:9]
	v_cmp_le_i32_e64 s[8:9], s37, v96
	s_nop 1
	v_cndmask_b32_e64 v10, 0, 1, s[8:9]
	v_or_b32_e32 v10, s12, v10
	v_ashrrev_i32_e32 v11, 31, v10
	v_lshlrev_b64 v[10:11], 18, v[10:11]
	v_lshl_add_u64 v[10:11], v[8:9], 0, v[10:11]
	v_lshl_add_u64 v[10:11], v[10:11], 0, v[98:99]
	global_load_dwordx2 v[236:237], v[10:11], off
	s_or_b64 exec, exec, s[2:3]
	v_cmp_ne_u32_e64 s[8:9], s37, v104
	s_and_saveexec_b64 s[2:3], s[8:9]
	v_cmp_le_i32_e64 s[8:9], s37, v104
	s_nop 1
	v_cndmask_b32_e64 v10, 0, 1, s[8:9]
	v_or_b32_e32 v10, s12, v10
	v_ashrrev_i32_e32 v11, 31, v10
	v_lshlrev_b64 v[10:11], 18, v[10:11]
	v_lshl_add_u64 v[10:11], v[8:9], 0, v[10:11]
	v_lshl_add_u64 v[10:11], v[10:11], 0, v[106:107]
	global_load_dwordx2 v[238:239], v[10:11], off
	s_or_b64 exec, exec, s[2:3]
	v_cmp_ne_u32_e64 s[8:9], s37, v112
	s_and_saveexec_b64 s[2:3], s[8:9]
	v_cmp_le_i32_e64 s[8:9], s37, v112
	s_nop 1
	v_cndmask_b32_e64 v10, 0, 1, s[8:9]
	v_or_b32_e32 v10, s12, v10
	v_ashrrev_i32_e32 v11, 31, v10
	v_lshlrev_b64 v[10:11], 18, v[10:11]
	v_lshl_add_u64 v[10:11], v[8:9], 0, v[10:11]
	v_lshl_add_u64 v[10:11], v[10:11], 0, v[114:115]
	global_load_dwordx2 v[240:241], v[10:11], off
	s_or_b64 exec, exec, s[2:3]
	v_cmp_ne_u32_e64 s[8:9], s37, v120
	s_and_saveexec_b64 s[2:3], s[8:9]
	v_cmp_le_i32_e64 s[8:9], s37, v120
	s_nop 1
	v_cndmask_b32_e64 v10, 0, 1, s[8:9]
	v_or_b32_e32 v10, s12, v10
	v_ashrrev_i32_e32 v11, 31, v10
	v_lshlrev_b64 v[10:11], 18, v[10:11]
	v_lshl_add_u64 v[10:11], v[8:9], 0, v[10:11]
	v_lshl_add_u64 v[10:11], v[10:11], 0, v[122:123]
	global_load_dwordx2 v[242:243], v[10:11], off
	s_or_b64 exec, exec, s[2:3]
	v_cmp_ne_u32_e64 s[8:9], s37, v128
	s_and_saveexec_b64 s[2:3], s[8:9]
	v_cmp_le_i32_e64 s[8:9], s37, v128
	s_nop 1
	v_cndmask_b32_e64 v10, 0, 1, s[8:9]
	v_or_b32_e32 v10, s12, v10
	v_ashrrev_i32_e32 v11, 31, v10
	v_lshlrev_b64 v[10:11], 18, v[10:11]
	v_lshl_add_u64 v[10:11], v[8:9], 0, v[10:11]
	v_lshl_add_u64 v[10:11], v[10:11], 0, v[130:131]
	global_load_dwordx2 v[244:245], v[10:11], off
	s_or_b64 exec, exec, s[2:3]
	v_cmp_ne_u32_e64 s[8:9], s37, v136
	s_and_saveexec_b64 s[2:3], s[8:9]
	v_cmp_le_i32_e64 s[8:9], s37, v136
	s_nop 1
	v_cndmask_b32_e64 v10, 0, 1, s[8:9]
	v_or_b32_e32 v10, s12, v10
	v_ashrrev_i32_e32 v11, 31, v10
	v_lshlrev_b64 v[10:11], 18, v[10:11]
	v_lshl_add_u64 v[10:11], v[8:9], 0, v[10:11]
	v_lshl_add_u64 v[10:11], v[10:11], 0, v[138:139]
	global_load_dwordx2 v[246:247], v[10:11], off
	s_or_b64 exec, exec, s[2:3]
	s_waitcnt vmcnt(0)
	v_cmp_ne_u32_e64 s[8:9], s37, v76
	s_and_saveexec_b64 s[2:3], s[8:9]
	ds_write_b64 v12, v[216:217] offset:8192
	s_or_b64 exec, exec, s[2:3]
	v_cmp_ne_u32_e64 s[8:9], s37, v84
	s_and_saveexec_b64 s[2:3], s[8:9]
	ds_write_b64 v81, v[218:219] offset:8192
	s_or_b64 exec, exec, s[2:3]
	v_cmp_ne_u32_e64 s[8:9], s37, v92
	s_and_saveexec_b64 s[2:3], s[8:9]
	ds_write_b64 v89, v[220:221] offset:8192
	s_or_b64 exec, exec, s[2:3]
	v_cmp_ne_u32_e64 s[8:9], s37, v100
	s_and_saveexec_b64 s[2:3], s[8:9]
	ds_write_b64 v97, v[222:223] offset:8192
	s_or_b64 exec, exec, s[2:3]
	v_cmp_ne_u32_e64 s[8:9], s37, v108
	s_and_saveexec_b64 s[2:3], s[8:9]
	ds_write_b64 v105, v[224:225] offset:8192
	s_or_b64 exec, exec, s[2:3]
	v_cmp_ne_u32_e64 s[8:9], s37, v116
	s_and_saveexec_b64 s[2:3], s[8:9]
	ds_write_b64 v113, v[226:227] offset:8192
	s_or_b64 exec, exec, s[2:3]
	v_cmp_ne_u32_e64 s[8:9], s37, v124
	s_and_saveexec_b64 s[2:3], s[8:9]
	ds_write_b64 v121, v[228:229] offset:8192
	s_or_b64 exec, exec, s[2:3]
	v_cmp_ne_u32_e64 s[8:9], s37, v132
	s_and_saveexec_b64 s[2:3], s[8:9]
	ds_write_b64 v129, v[230:231] offset:8192
	s_or_b64 exec, exec, s[2:3]
	v_cmp_ne_u32_e64 s[8:9], s37, v80
	s_and_saveexec_b64 s[2:3], s[8:9]
	ds_write_b64 v77, v[232:233] offset:8192
	s_or_b64 exec, exec, s[2:3]
	v_cmp_ne_u32_e64 s[8:9], s37, v88
	s_and_saveexec_b64 s[2:3], s[8:9]
	ds_write_b64 v85, v[234:235] offset:8192
	s_or_b64 exec, exec, s[2:3]
	v_cmp_ne_u32_e64 s[8:9], s37, v96
	s_and_saveexec_b64 s[2:3], s[8:9]
	ds_write_b64 v93, v[236:237] offset:8192
	s_or_b64 exec, exec, s[2:3]
	v_cmp_ne_u32_e64 s[8:9], s37, v104
	s_and_saveexec_b64 s[2:3], s[8:9]
	ds_write_b64 v101, v[238:239] offset:8192
	s_or_b64 exec, exec, s[2:3]
	v_cmp_ne_u32_e64 s[8:9], s37, v112
	s_and_saveexec_b64 s[2:3], s[8:9]
	ds_write_b64 v109, v[240:241] offset:8192
	s_or_b64 exec, exec, s[2:3]
	v_cmp_ne_u32_e64 s[8:9], s37, v120
	s_and_saveexec_b64 s[2:3], s[8:9]
	ds_write_b64 v117, v[242:243] offset:8192
	s_or_b64 exec, exec, s[2:3]
	v_cmp_ne_u32_e64 s[8:9], s37, v128
	s_and_saveexec_b64 s[2:3], s[8:9]
	ds_write_b64 v125, v[244:245] offset:8192
	s_or_b64 exec, exec, s[2:3]
	v_cmp_ne_u32_e64 s[8:9], s37, v136
	s_and_saveexec_b64 s[2:3], s[8:9]
	ds_write_b64 v133, v[246:247] offset:8192
	s_or_b64 exec, exec, s[2:3]

.LBB0_383:
	s_bfe_u32 s25, s0, 0x60003
	s_mov_b64 s[6:7], s[74:75]
	s_waitcnt lgkmcnt(0)
	s_barrier
	s_lshl_b32 s28, s25, 6
	v_lshlrev_b32_e32 v144, 1, v78
	s_add_i32 s29, s28, -2
	v_lshl_add_u64 v[8:9], s[6:7], 0, v[144:145]
	s_mov_b64 s[6:7], 0x91e0000
	s_ashr_i32 s26, s0, 9
	v_lshl_add_u64 v[48:49], v[8:9], 0, s[6:7]
	v_add_u32_e32 v50, s29, v79
	s_waitcnt vmcnt(0)
	v_mov_b64_e32 v[14:15], v[6:7]
	s_lshl_b32 s27, s26, 12
	v_cmp_gt_u32_e32 vcc, s67, v50
	v_mov_b64_e32 v[12:13], v[4:5]
	v_mov_b64_e32 v[10:11], v[2:3]
	v_mov_b64_e32 v[8:9], v[0:1]
	v_mov_b64_e32 v[216:217], 0
	v_mov_b64_e32 v[218:219], 0
	s_and_saveexec_b64 s[6:7], vcc
	v_or_b32_e32 v232, s27, v50
	v_ashrrev_i32_e32 v233, 31, v232
	v_lshlrev_b64 v[232:233], 10, v[232:233]
	v_lshl_add_u64 v[232:233], v[48:49], 0, v[232:233]
	global_load_dwordx4 v[216:219], v[232:233], off
	s_or_b64 exec, exec, s[6:7]
	v_add_u32_e32 v51, 1, v50
	v_cmp_gt_u32_e32 vcc, s67, v51
	v_mov_b64_e32 v[220:221], 0
	v_mov_b64_e32 v[222:223], 0
	s_and_saveexec_b64 s[6:7], vcc
	v_or_b32_e32 v234, s27, v51
	v_ashrrev_i32_e32 v235, 31, v234
	v_lshlrev_b64 v[234:235], 10, v[234:235]
	v_lshl_add_u64 v[234:235], v[48:49], 0, v[234:235]
	global_load_dwordx4 v[220:223], v[234:235], off
	s_or_b64 exec, exec, s[6:7]
	v_add_u32_e32 v51, s28, v79
	v_cmp_gt_u32_e32 vcc, s67, v51
	v_mov_b64_e32 v[224:225], 0
	v_mov_b64_e32 v[226:227], 0
	s_and_saveexec_b64 s[6:7], vcc
	v_or_b32_e32 v236, s27, v51
	v_ashrrev_i32_e32 v237, 31, v236
	v_lshlrev_b64 v[236:237], 10, v[236:237]
	v_lshl_add_u64 v[236:237], v[48:49], 0, v[236:237]
	global_load_dwordx4 v[224:227], v[236:237], off
	s_or_b64 exec, exec, s[6:7]
	v_add_u32_e32 v50, 3, v50
	v_cmp_gt_u32_e32 vcc, s67, v50
	v_mov_b64_e32 v[228:229], 0
	v_mov_b64_e32 v[230:231], 0
	s_and_saveexec_b64 s[6:7], vcc
	v_or_b32_e32 v238, s27, v50
	v_ashrrev_i32_e32 v239, 31, v238
	v_lshlrev_b64 v[238:239], 10, v[238:239]
	v_lshl_add_u64 v[238:239], v[48:49], 0, v[238:239]
	global_load_dwordx4 v[228:231], v[238:239], off
	s_or_b64 exec, exec, s[6:7]
	v_add_u32_e32 v50, s29, v80
	v_cmp_gt_u32_e32 vcc, s67, v50
	v_mov_b64_e32 v[104:105], 0
	v_mov_b64_e32 v[106:107], 0
	s_and_saveexec_b64 s[6:7], vcc
	v_or_b32_e32 v232, s27, v50
	v_ashrrev_i32_e32 v233, 31, v232
	v_lshlrev_b64 v[232:233], 10, v[232:233]
	v_lshl_add_u64 v[232:233], v[48:49], 0, v[232:233]
	global_load_dwordx4 v[104:107], v[232:233], off
	s_or_b64 exec, exec, s[6:7]
	v_add_u32_e32 v51, 1, v50
	v_cmp_gt_u32_e32 vcc, s67, v51
	v_mov_b64_e32 v[108:109], 0
	v_mov_b64_e32 v[110:111], 0
	s_and_saveexec_b64 s[6:7], vcc
	v_or_b32_e32 v234, s27, v51
	v_ashrrev_i32_e32 v235, 31, v234
	v_lshlrev_b64 v[234:235], 10, v[234:235]
	v_lshl_add_u64 v[234:235], v[48:49], 0, v[234:235]
	global_load_dwordx4 v[108:111], v[234:235], off
	s_or_b64 exec, exec, s[6:7]
	v_add_u32_e32 v51, s28, v80
	v_cmp_gt_u32_e32 vcc, s67, v51
	v_mov_b64_e32 v[112:113], 0
	v_mov_b64_e32 v[114:115], 0
	s_and_saveexec_b64 s[6:7], vcc
	v_or_b32_e32 v236, s27, v51
	v_ashrrev_i32_e32 v237, 31, v236
	v_lshlrev_b64 v[236:237], 10, v[236:237]
	v_lshl_add_u64 v[236:237], v[48:49], 0, v[236:237]
	global_load_dwordx4 v[112:115], v[236:237], off
	s_or_b64 exec, exec, s[6:7]
	v_add_u32_e32 v50, 3, v50
	v_cmp_gt_u32_e32 vcc, s67, v50
	v_mov_b64_e32 v[116:117], 0
	v_mov_b64_e32 v[118:119], 0
	s_and_saveexec_b64 s[6:7], vcc
	v_or_b32_e32 v238, s27, v50
	v_ashrrev_i32_e32 v239, 31, v238
	v_lshlrev_b64 v[238:239], 10, v[238:239]
	v_lshl_add_u64 v[238:239], v[48:49], 0, v[238:239]
	global_load_dwordx4 v[116:119], v[238:239], off
	s_or_b64 exec, exec, s[6:7]
	s_waitcnt vmcnt(4)
	v_lshlrev_b32_e32 v52, 16, v216
	v_and_b32_e32 v53, 0xffff0000, v216
	v_lshlrev_b32_e32 v8, 16, v217
	v_and_b32_e32 v9, 0xffff0000, v217
	v_lshlrev_b32_e32 v12, 16, v218
	v_and_b32_e32 v13, 0xffff0000, v218
	v_lshlrev_b32_e32 v10, 16, v219
	v_and_b32_e32 v11, 0xffff0000, v219
	v_pk_fma_f32 v[14:15], v[22:23], v[10:11], v[6:7]
	v_pk_fma_f32 v[12:13], v[20:21], v[12:13], v[4:5]
	v_pk_fma_f32 v[10:11], v[18:19], v[8:9], v[2:3]
	v_pk_fma_f32 v[8:9], v[16:17], v[52:53], v[0:1]
	v_lshlrev_b32_e32 v56, 16, v220
	v_and_b32_e32 v57, 0xffff0000, v220
	v_lshlrev_b32_e32 v52, 16, v221
	v_and_b32_e32 v53, 0xffff0000, v221
	v_lshlrev_b32_e32 v58, 16, v222
	v_and_b32_e32 v59, 0xffff0000, v222
	v_lshlrev_b32_e32 v54, 16, v223
	v_and_b32_e32 v55, 0xffff0000, v223
	v_pk_fma_f32 v[14:15], v[30:31], v[54:55], v[14:15]
	v_pk_fma_f32 v[12:13], v[28:29], v[58:59], v[12:13]
	v_pk_fma_f32 v[10:11], v[26:27], v[52:53], v[10:11]
	v_pk_fma_f32 v[8:9], v[24:25], v[56:57], v[8:9]
	v_lshlrev_b32_e32 v56, 16, v224
	v_and_b32_e32 v57, 0xffff0000, v224
	v_lshlrev_b32_e32 v52, 16, v225
	v_and_b32_e32 v53, 0xffff0000, v225
	v_lshlrev_b32_e32 v58, 16, v226
	v_and_b32_e32 v59, 0xffff0000, v226
	v_lshlrev_b32_e32 v54, 16, v227
	v_and_b32_e32 v55, 0xffff0000, v227
	v_pk_fma_f32 v[14:15], v[38:39], v[54:55], v[14:15]
	v_pk_fma_f32 v[12:13], v[36:37], v[58:59], v[12:13]
	v_pk_fma_f32 v[10:11], v[34:35], v[52:53], v[10:11]
	v_pk_fma_f32 v[8:9], v[32:33], v[56:57], v[8:9]
	v_lshlrev_b32_e32 v54, 16, v228
	v_and_b32_e32 v55, 0xffff0000, v228
	v_lshlrev_b32_e32 v50, 16, v229
	v_and_b32_e32 v51, 0xffff0000, v229
	v_lshlrev_b32_e32 v56, 16, v230
	v_and_b32_e32 v57, 0xffff0000, v230
	v_lshlrev_b32_e32 v52, 16, v231
	v_and_b32_e32 v53, 0xffff0000, v231
	v_pk_fma_f32 v[14:15], v[46:47], v[52:53], v[14:15]
	v_pk_fma_f32 v[12:13], v[44:45], v[56:57], v[12:13]
	v_pk_fma_f32 v[10:11], v[42:43], v[50:51], v[10:11]
	v_pk_fma_f32 v[8:9], v[40:41], v[54:55], v[8:9]
	v_cvt_pk_bf16_f32 v8, v8, v9
	v_cvt_pk_bf16_f32 v9, v10, v11
	v_cvt_pk_bf16_f32 v10, v12, v13
	v_cvt_pk_bf16_f32 v11, v14, v15
	ds_write_b128 v81, v[8:11]
	v_mov_b64_e32 v[14:15], v[6:7]
	v_mov_b64_e32 v[12:13], v[4:5]
	v_mov_b64_e32 v[10:11], v[2:3]
	v_mov_b64_e32 v[8:9], v[0:1]
	s_waitcnt vmcnt(0)
	v_lshlrev_b32_e32 v52, 16, v104
	v_and_b32_e32 v53, 0xffff0000, v104
	v_lshlrev_b32_e32 v8, 16, v105
	v_and_b32_e32 v9, 0xffff0000, v105
	v_lshlrev_b32_e32 v12, 16, v106
	v_and_b32_e32 v13, 0xffff0000, v106
	v_lshlrev_b32_e32 v10, 16, v107
	v_and_b32_e32 v11, 0xffff0000, v107
	v_pk_fma_f32 v[14:15], v[22:23], v[10:11], v[6:7]
	v_pk_fma_f32 v[12:13], v[20:21], v[12:13], v[4:5]
	v_pk_fma_f32 v[10:11], v[18:19], v[8:9], v[2:3]
	v_pk_fma_f32 v[8:9], v[16:17], v[52:53], v[0:1]
	v_lshlrev_b32_e32 v56, 16, v108
	v_and_b32_e32 v57, 0xffff0000, v108
	v_lshlrev_b32_e32 v52, 16, v109
	v_and_b32_e32 v53, 0xffff0000, v109
	v_lshlrev_b32_e32 v58, 16, v110
	v_and_b32_e32 v59, 0xffff0000, v110
	v_lshlrev_b32_e32 v54, 16, v111
	v_and_b32_e32 v55, 0xffff0000, v111
	v_pk_fma_f32 v[14:15], v[30:31], v[54:55], v[14:15]
	v_pk_fma_f32 v[12:13], v[28:29], v[58:59], v[12:13]
	v_pk_fma_f32 v[10:11], v[26:27], v[52:53], v[10:11]
	v_pk_fma_f32 v[8:9], v[24:25], v[56:57], v[8:9]
	v_lshlrev_b32_e32 v56, 16, v112
	v_and_b32_e32 v57, 0xffff0000, v112
	v_lshlrev_b32_e32 v52, 16, v113
	v_and_b32_e32 v53, 0xffff0000, v113
	v_lshlrev_b32_e32 v58, 16, v114
	v_and_b32_e32 v59, 0xffff0000, v114
	v_lshlrev_b32_e32 v54, 16, v115
	v_and_b32_e32 v55, 0xffff0000, v115
	v_pk_fma_f32 v[14:15], v[38:39], v[54:55], v[14:15]
	v_pk_fma_f32 v[12:13], v[36:37], v[58:59], v[12:13]
	v_pk_fma_f32 v[10:11], v[34:35], v[52:53], v[10:11]
	v_pk_fma_f32 v[8:9], v[32:33], v[56:57], v[8:9]
	v_lshlrev_b32_e32 v52, 16, v116
	v_and_b32_e32 v53, 0xffff0000, v116
	v_lshlrev_b32_e32 v48, 16, v117
	v_and_b32_e32 v49, 0xffff0000, v117
	v_lshlrev_b32_e32 v54, 16, v118
	v_and_b32_e32 v55, 0xffff0000, v118
	v_lshlrev_b32_e32 v50, 16, v119
	v_and_b32_e32 v51, 0xffff0000, v119
	v_pk_fma_f32 v[14:15], v[46:47], v[50:51], v[14:15]
	v_pk_fma_f32 v[12:13], v[44:45], v[54:55], v[12:13]
	v_pk_fma_f32 v[10:11], v[42:43], v[48:49], v[10:11]
	v_pk_fma_f32 v[8:9], v[40:41], v[52:53], v[8:9]
	v_mov_b32_e32 v83, v191
	v_cvt_pk_bf16_f32 v8, v8, v9
	v_cvt_pk_bf16_f32 v9, v10, v11
	v_cvt_pk_bf16_f32 v10, v12, v13
	v_cvt_pk_bf16_f32 v11, v14, v15
	ds_write_b128 v82, v[8:11]
	s_waitcnt lgkmcnt(0)
	s_barrier
	v_mov_b32_e32 v85, v191
	v_and_b32_e32 v87, 15, v83
	v_lshrrev_b32_e32 v96, 4, v83
	v_bfe_u32 v97, v83, 4, 2
	s_mov_b64 s[6:7], s[74:75]
	v_bfe_u32 v86, v83, 1, 3
	v_ashrrev_i32_e32 v84, 6, v83
	v_lshlrev_b32_e32 v76, 7, v87
	v_bitop3_b32 v8, v96, v86, 3 bitop3:0x6c
	v_bitop3_b32 v13, v97, v86, 4 bitop3:0x36
	v_lshl_or_b32 v12, v84, 11, v76
	v_lshlrev_b32_e32 v8, 4, v8
	v_lshlrev_b32_e32 v13, 4, v13
	s_add_u32 s6, s6, s2
	v_add3_u32 v8, s60, v8, v12
	v_add3_u32 v12, s60, v13, v12
	s_addc_u32 s7, s7, 0
	v_lshlrev_b32_e32 v144, 4, v97
	ds_read_b128 v[8:11], v8
	ds_read_b128 v[72:75], v12
	v_lshl_add_u64 v[12:13], s[6:7], 0, v[144:145]
	s_mov_b64 s[6:7], 0x3980000
	v_lshl_add_u64 v[92:93], v[12:13], 0, s[6:7]
	s_mov_b64 s[6:7], 0x39a0000
	v_mov_b32_e32 v77, v145
	v_lshl_add_u64 v[94:95], v[12:13], 0, s[6:7]
	v_mul_u32_u24_e32 v184, 0xf0, v97
	v_lshl_add_u32 v184, v87, 4, v184
	v_mov_b32_e32 v185, v145
	v_lshl_add_u64 v[60:61], v[92:93], 0, v[184:185]
	v_lshl_add_u64 v[62:63], v[94:95], 0, v[184:185]
	s_mov_b64 s[98:99], 0x1000
	v_lshl_add_u64 v[180:181], v[60:61], 0, s[98:99]
	v_lshl_add_u64 v[182:183], v[62:63], 0, s[98:99]
	global_load_dwordx4 v[104:107], v[180:181], off offset:-4096
	global_load_dwordx4 v[108:111], v[182:183], off offset:-4096
	global_load_dwordx4 v[112:115], v[180:181], off offset:-3072
	global_load_dwordx4 v[116:119], v[182:183], off offset:-3072
	global_load_dwordx4 v[120:123], v[180:181], off offset:-2048
	global_load_dwordx4 v[124:127], v[182:183], off offset:-2048
	global_load_dwordx4 v[128:131], v[180:181], off offset:-1024
	global_load_dwordx4 v[132:135], v[182:183], off offset:-1024
	global_load_dwordx4 v[136:139], v[180:181], off
	global_load_dwordx4 v[140:143], v[182:183], off
	global_load_dwordx4 v[156:159], v[180:181], off offset:1024
	global_load_dwordx4 v[160:163], v[182:183], off offset:1024
	global_load_dwordx4 v[164:167], v[180:181], off offset:2048
	global_load_dwordx4 v[168:171], v[182:183], off offset:2048
	global_load_dwordx4 v[172:175], v[180:181], off offset:3072
	global_load_dwordx4 v[176:179], v[182:183], off offset:3072
	v_lshrrev_b32_e32 v98, 1, v83
	v_readlane_b32 s36, v254, 22
	v_readlane_b32 s40, v254, 26
	v_readlane_b32 s41, v254, 27
	s_mov_b64 s[6:7], s[40:41]
	v_readlane_b32 s44, v254, 30
	v_readlane_b32 s45, v254, 31
	s_mov_b32 s27, 0x122e6000
	s_mov_b32 s28, 0xc1000000
	v_readlane_b32 s37, v254, 23
	v_readlane_b32 s38, v254, 24
	v_readlane_b32 s39, v254, 25
	v_readlane_b32 s42, v254, 28
	v_readlane_b32 s43, v254, 29
	v_readlane_b32 s46, v254, 32
	v_readlane_b32 s47, v254, 33
	v_readlane_b32 s48, v254, 34
	v_readlane_b32 s49, v254, 35
	v_readlane_b32 s50, v254, 36
	v_readlane_b32 s51, v254, 37
	v_lshlrev_b32_e32 v154, 2, v97
	v_or_b32_e32 v154, s8, v154
	v_ashrrev_i32_e32 v155, 31, v154
	v_lshlrev_b64 v[154:155], 2, v[154:155]
	s_add_u32 s98, s74, s3
	s_addc_u32 s99, s75, 0
	s_add_u32 s98, s98, 0x122e6000
	s_addc_u32 s99, s99, 0
	v_lshl_add_u64 v[184:185], s[98:99], 0, v[144:145]
	v_lshl_add_u64 v[180:181], s[40:41], 0, v[154:155]
	v_lshl_add_u64 v[146:147], s[44:45], 0, v[154:155]
	global_load_dwordx4 v[216:219], v[180:181], off
	global_load_dwordx4 v[220:223], v[146:147], off
	global_load_dwordx4 v[224:227], v[184:185], off
	global_load_dwordx4 v[228:231], v[180:181], off offset:64
	global_load_dwordx4 v[232:235], v[146:147], off offset:64
	global_load_dwordx4 v[236:239], v[184:185], off offset:64
	global_load_dwordx4 v[240:243], v[180:181], off offset:128
	global_load_dwordx4 v[244:247], v[146:147], off offset:128
	global_load_dwordx4 v[248:251], v[184:185], off offset:128
	global_load_dwordx4 v[180:183], v[180:181], off offset:192
	global_load_dwordx4 v[146:149], v[146:147], off offset:192
	s_waitcnt vmcnt(0) lgkmcnt(0)
	v_mfma_f32_16x16x32_bf16 v[12:15], v[104:107], v[8:11], 0
	v_mfma_f32_16x16x32_bf16 v[48:51], v[108:111], v[8:11], 0
	v_mfma_f32_16x16x32_bf16 v[68:71], v[112:115], v[72:75], v[12:15]
	v_mfma_f32_16x16x32_bf16 v[64:67], v[116:119], v[72:75], v[48:51]
	s_nop 4
	v_mfma_f32_16x16x32_bf16 v[12:15], v[120:123], v[8:11], 0
	v_mfma_f32_16x16x32_bf16 v[48:51], v[124:127], v[8:11], 0
	v_mfma_f32_16x16x32_bf16 v[60:63], v[128:131], v[72:75], v[12:15]
	s_nop 5
	v_or_b32_e32 v12, 0x1000, v76
	v_mov_b32_e32 v13, v145
	v_lshl_add_u64 v[52:53], v[92:93], 0, v[12:13]
	v_mfma_f32_16x16x32_bf16 v[56:59], v[132:135], v[72:75], v[48:51]
	v_lshl_add_u64 v[88:89], v[94:95], 0, v[12:13]
	s_nop 0
	s_nop 0
	s_nop 0
	v_mfma_f32_16x16x32_bf16 v[12:15], v[136:139], v[8:11], 0
	v_mfma_f32_16x16x32_bf16 v[48:51], v[140:143], v[8:11], 0
	v_mfma_f32_16x16x32_bf16 v[52:55], v[156:159], v[72:75], v[12:15]
	s_nop 5
	v_or_b32_e32 v12, 0x1800, v76
	v_mov_b32_e32 v13, v145
	v_lshl_add_u64 v[76:77], v[92:93], 0, v[12:13]
	v_mfma_f32_16x16x32_bf16 v[48:51], v[160:163], v[72:75], v[48:51]
	v_lshl_add_u64 v[92:93], v[94:95], 0, v[12:13]
	v_mfma_f32_16x16x32_bf16 v[12:15], v[164:167], v[8:11], 0
	v_mfma_f32_16x16x32_bf16 v[8:11], v[168:171], v[8:11], 0
	s_nop 0
	v_lshlrev_b32_e32 v76, 2, v97
	v_mov_b32_e32 v77, v145
	v_mfma_f32_16x16x32_bf16 v[12:15], v[172:175], v[72:75], v[12:15]
	v_bfe_u32 v88, v96, 1, 1
	v_mfma_f32_16x16x32_bf16 v[8:11], v[176:179], v[72:75], v[8:11]
	global_load_dwordx4 v[104:107], v[184:185], off offset:192
	v_lshl_or_b32 v72, v84, 4, v87
	v_lshlrev_b32_e32 v87, 7, v72
	v_and_b32_e32 v73, 8, v98
	v_lshlrev_b32_e32 v102, 8, v72
	v_or_b32_e32 v72, s8, v76
	v_add_u32_e32 v89, s60, v73
	v_ashrrev_i32_e32 v73, 31, v72
	v_lshlrev_b64 v[90:91], 2, v[72:73]
	v_lshl_add_u64 v[72:73], s[6:7], 0, v[90:91]
	s_mov_b64 s[6:7], s[44:45]
	v_bitop3_b32 v98, v88, v98, 7 bitop3:0x78
	v_lshl_add_u64 v[90:91], s[6:7], 0, v[90:91]
	s_mov_b64 s[6:7], s[74:75]
	s_add_u32 s6, s6, s3
	s_addc_u32 s7, s7, 0
	v_lshl_add_u64 v[94:95], s[6:7], 0, v[144:145]
	v_add_co_u32_e32 v94, vcc, s27, v94
	v_lshlrev_b32_e32 v98, 4, v98
	s_nop 0
	v_addc_co_u32_e32 v95, vcc, 0, v95, vcc
	v_add3_u32 v98, v89, v98, v87
	ds_read_b64 v[98:99], v98
	s_waitcnt lgkmcnt(0)
	v_lshlrev_b32_e32 v100, 16, v98
	v_and_b32_e32 v101, 0xffff0000, v98
	v_lshlrev_b32_e32 v98, 16, v99
	v_and_b32_e32 v99, 0xffff0000, v99
	v_add_f32_e32 v68, v68, v216
	v_add_f32_e32 v69, v69, v217
	v_mul_f32_e32 v68, 0xbfb8aa3b, v68
	v_mul_f32_e32 v69, 0xbfb8aa3b, v69
	v_exp_f32_e32 v68, v68
	v_exp_f32_e32 v69, v69
	v_add_f32_e32 v64, v64, v220
	v_add_f32_e32 v65, v65, v221
	v_add_f32_e32 v68, 1.0, v68
	v_add_f32_e32 v69, 1.0, v69
	v_rcp_f32_e32 v68, v68
	v_rcp_f32_e32 v69, v69
	v_add_f32_e32 v70, v70, v218
	v_add_f32_e32 v71, v71, v219
	v_mul_f32_e32 v70, 0xbfb8aa3b, v70
	v_pk_mul_f32 v[68:69], v[68:69], s[28:29] op_sel_hi:[1,0]
	v_mul_f32_e32 v71, 0xbfb8aa3b, v71
	v_pk_mul_f32 v[72:73], v[224:225], v[68:69]
	v_exp_f32_e32 v70, v70
	v_pk_add_f32 v[90:91], v[72:73], v[72:73]
	v_mul_f32_e32 v68, 0x3fb8aa3b, v72
	v_fmamk_f32 v69, v90, 0x3ab60b61, v195
	v_exp_f32_e32 v68, v68
	v_fmaak_f32 v69, v90, v69, 0x3d2aaaab
	v_fmaak_f32 v69, v90, v69, 0x3e2aaaab
	v_exp_f32_e32 v71, v71
	v_fma_f32 v69, v90, v69, 0.5
	v_fma_f32 v69, v90, v69, 1.0
	v_mul_f32_e64 v69, v69, -v90
	v_fma_f32 v72, -v68, v68, 1.0
	v_cmp_lt_f32_e64 s[6:7], s84, v90
	v_add_f32_e32 v70, 1.0, v70
	v_add_f32_e32 v71, 1.0, v71
	v_cndmask_b32_e64 v69, v72, v69, s[6:7]
	v_sqrt_f32_e32 v72, v69
	v_mul_f32_e32 v69, 0x3fb8aa3b, v73
	v_fmamk_f32 v73, v91, 0x3ab60b61, v195
	v_rcp_f32_e32 v70, v70
	v_rcp_f32_e32 v71, v71
	v_exp_f32_e32 v69, v69
	v_fmaak_f32 v73, v91, v73, 0x3d2aaaab
	v_fmaak_f32 v73, v91, v73, 0x3e2aaaab
	v_fma_f32 v73, v91, v73, 0.5
	v_fma_f32 v73, v91, v73, 1.0
	v_pk_mul_f32 v[70:71], v[70:71], s[28:29] op_sel_hi:[1,0]
	v_cmp_lt_f32_e32 vcc, s84, v91
	v_mul_f32_e64 v73, v73, -v91
	v_fma_f32 v90, -v69, v69, 1.0
	v_pk_mul_f32 v[74:75], v[226:227], v[70:71]
	v_cndmask_b32_e32 v73, v90, v73, vcc
	v_pk_add_f32 v[90:91], v[74:75], v[74:75]
	v_mul_f32_e32 v70, 0x3fb8aa3b, v74
	v_fmamk_f32 v71, v90, 0x3ab60b61, v195
	v_exp_f32_e32 v70, v70
	v_fmaak_f32 v71, v90, v71, 0x3d2aaaab
	v_fmaak_f32 v71, v90, v71, 0x3e2aaaab
	v_fma_f32 v71, v90, v71, 0.5
	v_fma_f32 v71, v90, v71, 1.0
	v_mul_f32_e64 v71, v71, -v90
	v_fma_f32 v74, -v70, v70, 1.0
	v_cmp_lt_f32_e64 s[6:7], s84, v90
	v_add_f32_e32 v66, v66, v222
	v_add_f32_e32 v67, v67, v223
	v_cndmask_b32_e64 v71, v74, v71, s[6:7]
	v_sqrt_f32_e32 v74, v71
	v_mul_f32_e32 v71, 0x3fb8aa3b, v75
	v_fmamk_f32 v75, v91, 0x3ab60b61, v195
	v_mul_f32_e32 v64, 0xbfb8aa3b, v64
	v_mul_f32_e32 v65, 0xbfb8aa3b, v65
	v_mul_f32_e32 v66, 0xbfb8aa3b, v66
	v_mul_f32_e32 v67, 0xbfb8aa3b, v67
	v_exp_f32_e32 v71, v71
	v_fmaak_f32 v75, v91, v75, 0x3d2aaaab
	v_exp_f32_e32 v64, v64
	v_exp_f32_e32 v65, v65
	v_exp_f32_e32 v66, v66
	v_exp_f32_e32 v67, v67
	v_fmaak_f32 v75, v91, v75, 0x3e2aaaab
	v_fma_f32 v75, v91, v75, 0.5
	v_fma_f32 v75, v91, v75, 1.0
	v_cmp_lt_f32_e32 vcc, s84, v91
	v_mul_f32_e64 v75, v75, -v91
	v_fma_f32 v90, -v71, v71, 1.0
	v_add_f32_e32 v64, 1.0, v64
	v_add_f32_e32 v65, 1.0, v65
	v_add_f32_e32 v66, 1.0, v66
	v_add_f32_e32 v67, 1.0, v67
	v_cndmask_b32_e32 v75, v90, v75, vcc
	v_rcp_f32_e32 v64, v64
	v_rcp_f32_e32 v65, v65
	v_sqrt_f32_e32 v73, v73
	v_rcp_f32_e32 v66, v66
	v_rcp_f32_e32 v67, v67
	v_sqrt_f32_e32 v75, v75
	v_pk_mul_f32 v[64:65], v[64:65], v[72:73]
	s_mov_b64 s[6:7], s[40:41]
	v_pk_mul_f32 v[72:73], v[64:65], v[100:101]
	v_pk_mul_f32 v[66:67], v[66:67], v[74:75]
	v_lshl_add_u64 v[64:65], v[76:77], 0, s[8:9]
	v_pk_mul_f32 v[74:75], v[66:67], v[98:99]
	v_add3_u32 v66, s60, v102, v144
	ds_write_b128 v66, v[68:71] offset:8192
	ds_write_b128 v66, v[72:75] offset:24576
	v_lshlrev_b64 v[64:65], 2, v[64:65]
	v_lshl_add_u64 v[68:69], s[6:7], 0, v[64:65]
	s_mov_b64 s[6:7], s[44:45]
	v_bitop3_b32 v67, v88, v86, 2 bitop3:0x36
	v_lshl_add_u64 v[72:73], s[6:7], 0, v[64:65]
	s_mov_b64 s[6:7], s[74:75]
	s_add_u32 s6, s6, s3
	s_addc_u32 s7, s7, 0
	v_lshl_add_u64 v[76:77], s[6:7], 0, v[144:145]
	v_add_co_u32_e32 v76, vcc, s27, v76
	v_lshlrev_b32_e32 v67, 4, v67
	s_nop 0
	v_addc_co_u32_e32 v77, vcc, 0, v77, vcc
	v_add3_u32 v67, v89, v67, v87
	ds_read_b64 v[76:77], v67
	s_waitcnt lgkmcnt(0)
	v_lshlrev_b32_e32 v94, 16, v76
	v_and_b32_e32 v95, 0xffff0000, v76
	v_lshlrev_b32_e32 v76, 16, v77
	v_and_b32_e32 v77, 0xffff0000, v77
	v_add_f32_e32 v60, v60, v228
	v_mul_f32_e32 v60, 0xbfb8aa3b, v60
	v_exp_f32_e32 v60, v60
	v_add_f32_e32 v62, v62, v230
	v_add_f32_e32 v56, v56, v232
	v_mul_f32_e32 v56, 0xbfb8aa3b, v56
	v_exp_f32_e32 v56, v56
	v_add_f32_e32 v58, v58, v234
	v_mul_f32_e32 v58, 0xbfb8aa3b, v58
	v_exp_f32_e32 v58, v58
	v_add_f32_e32 v56, 1.0, v56
	v_rcp_f32_e32 v68, v56
	v_add_f32_e32 v56, v61, v229
	v_mul_f32_e32 v56, 0xbfb8aa3b, v56
	v_exp_f32_e32 v56, v56
	v_add_f32_e32 v60, 1.0, v60
	v_rcp_f32_e32 v60, v60
	v_add_f32_e32 v58, 1.0, v58
	v_add_f32_e32 v56, 1.0, v56
	v_rcp_f32_e32 v61, v56
	v_add_f32_e32 v56, v57, v233
	v_mul_f32_e32 v56, 0xbfb8aa3b, v56
	v_exp_f32_e32 v56, v56
	v_rcp_f32_e32 v70, v58
	v_add_f32_e32 v58, v63, v231
	v_mul_f32_e32 v58, 0xbfb8aa3b, v58
	v_add_f32_e32 v56, 1.0, v56
	v_rcp_f32_e32 v69, v56
	v_pk_mul_f32 v[56:57], v[60:61], s[28:29] op_sel_hi:[1,0]
	v_exp_f32_e32 v58, v58
	v_pk_mul_f32 v[60:61], v[236:237], v[56:57]
	v_mul_f32_e32 v62, 0xbfb8aa3b, v62
	v_pk_add_f32 v[72:73], v[60:61], v[60:61]
	v_mul_f32_e32 v56, 0x3fb8aa3b, v60
	v_fmamk_f32 v57, v72, 0x3ab60b61, v195
	v_exp_f32_e32 v56, v56
	v_fmaak_f32 v57, v72, v57, 0x3d2aaaab
	v_exp_f32_e32 v62, v62
	v_fmaak_f32 v57, v72, v57, 0x3e2aaaab
	v_add_f32_e32 v58, 1.0, v58
	v_fma_f32 v57, v72, v57, 0.5
	v_rcp_f32_e32 v63, v58
	v_add_f32_e32 v58, v59, v235
	v_fma_f32 v57, v72, v57, 1.0
	v_mul_f32_e32 v58, 0xbfb8aa3b, v58
	v_mul_f32_e64 v57, v57, -v72
	v_fma_f32 v60, -v56, v56, 1.0
	v_cmp_lt_f32_e64 s[6:7], s84, v72
	v_add_f32_e32 v62, 1.0, v62
	v_exp_f32_e32 v58, v58
	v_cndmask_b32_e64 v57, v60, v57, s[6:7]
	v_rcp_f32_e32 v62, v62
	v_sqrt_f32_e32 v60, v57
	v_mul_f32_e32 v57, 0x3fb8aa3b, v61
	v_fmamk_f32 v61, v73, 0x3ab60b61, v195
	v_fmaak_f32 v61, v73, v61, 0x3d2aaaab
	v_fmaak_f32 v61, v73, v61, 0x3e2aaaab
	v_add_f32_e32 v58, 1.0, v58
	v_fma_f32 v61, v73, v61, 0.5
	v_rcp_f32_e32 v71, v58
	v_pk_mul_f32 v[58:59], v[62:63], s[28:29] op_sel_hi:[1,0]
	v_fma_f32 v61, v73, v61, 1.0
	v_pk_mul_f32 v[62:63], v[238:239], v[58:59]
	v_cmp_lt_f32_e32 vcc, s84, v73
	v_mul_f32_e64 v61, v61, -v73
	v_pk_add_f32 v[72:73], v[62:63], v[62:63]
	v_mul_f32_e32 v58, 0x3fb8aa3b, v62
	v_fmamk_f32 v59, v72, 0x3ab60b61, v195
	v_exp_f32_e32 v58, v58
	v_fmaak_f32 v59, v72, v59, 0x3d2aaaab
	v_fmaak_f32 v59, v72, v59, 0x3e2aaaab
	v_fma_f32 v59, v72, v59, 0.5
	v_fma_f32 v59, v72, v59, 1.0
	v_mul_f32_e64 v59, v59, -v72
	v_fma_f32 v62, -v58, v58, 1.0
	v_cmp_lt_f32_e64 s[6:7], s84, v72
	v_exp_f32_e32 v57, v57
	s_nop 0
	v_cndmask_b32_e64 v59, v62, v59, s[6:7]
	v_sqrt_f32_e32 v62, v59
	v_mul_f32_e32 v59, 0x3fb8aa3b, v63
	v_fmamk_f32 v63, v73, 0x3ab60b61, v195
	v_exp_f32_e32 v59, v59
	v_fmaak_f32 v63, v73, v63, 0x3d2aaaab
	v_fmaak_f32 v63, v73, v63, 0x3e2aaaab
	v_fma_f32 v63, v73, v63, 0.5
	v_fma_f32 v67, -v57, v57, 1.0
	v_fma_f32 v63, v73, v63, 1.0
	v_cndmask_b32_e32 v61, v67, v61, vcc
	v_cmp_lt_f32_e32 vcc, s84, v73
	v_mul_f32_e64 v63, v63, -v73
	v_fma_f32 v67, -v59, v59, 1.0
	v_cndmask_b32_e32 v63, v67, v63, vcc
	v_sqrt_f32_e32 v61, v61
	v_sqrt_f32_e32 v63, v63
	s_mov_b64 s[6:7], s[40:41]
	v_bitop3_b32 v67, v88, v86, 4 bitop3:0x36
	v_pk_mul_f32 v[60:61], v[68:69], v[60:61]
	v_pk_mul_f32 v[62:63], v[70:71], v[62:63]
	v_pk_mul_f32 v[60:61], v[60:61], v[94:95]
	v_pk_mul_f32 v[62:63], v[62:63], v[76:77]
	ds_write_b128 v66, v[56:59] offset:8256
	ds_write_b128 v66, v[60:63] offset:24640
	v_lshlrev_b32_e32 v67, 4, v67
	v_lshl_add_u64 v[56:57], s[6:7], 0, v[64:65]
	s_mov_b64 s[6:7], s[44:45]
	v_add3_u32 v67, v89, v67, v87
	v_lshl_add_u64 v[60:61], s[6:7], 0, v[64:65]
	s_mov_b64 s[6:7], s[74:75]
	s_add_u32 s6, s6, s3
	s_addc_u32 s7, s7, 0
	v_lshl_add_u64 v[68:69], s[6:7], 0, v[144:145]
	v_add_co_u32_e32 v68, vcc, s27, v68
	ds_read_b64 v[72:73], v67
	s_nop 0
	v_addc_co_u32_e32 v69, vcc, 0, v69, vcc
	s_waitcnt lgkmcnt(0)
	v_lshlrev_b32_e32 v74, 16, v72
	v_and_b32_e32 v75, 0xffff0000, v72
	v_lshlrev_b32_e32 v72, 16, v73
	v_and_b32_e32 v73, 0xffff0000, v73
	v_add_f32_e32 v52, v52, v240
	v_mul_f32_e32 v52, 0xbfb8aa3b, v52
	v_exp_f32_e32 v52, v52
	v_add_f32_e32 v54, v54, v242
	v_add_f32_e32 v48, v48, v244
	v_mul_f32_e32 v48, 0xbfb8aa3b, v48
	v_exp_f32_e32 v48, v48
	v_add_f32_e32 v50, v50, v246
	v_mul_f32_e32 v50, 0xbfb8aa3b, v50
	v_add_f32_e32 v52, 1.0, v52
	v_add_f32_e32 v48, 1.0, v48
	v_rcp_f32_e32 v56, v48
	v_add_f32_e32 v48, v53, v241
	v_mul_f32_e32 v48, 0xbfb8aa3b, v48
	v_exp_f32_e32 v48, v48
	v_exp_f32_e32 v50, v50
	v_rcp_f32_e32 v52, v52
	v_mul_f32_e32 v54, 0xbfb8aa3b, v54
	v_add_f32_e32 v48, 1.0, v48
	v_rcp_f32_e32 v53, v48
	v_add_f32_e32 v48, v49, v245
	v_mul_f32_e32 v48, 0xbfb8aa3b, v48
	v_exp_f32_e32 v48, v48
	v_add_f32_e32 v50, 1.0, v50
	v_rcp_f32_e32 v58, v50
	v_add_f32_e32 v50, v55, v243
	v_add_f32_e32 v48, 1.0, v48
	v_rcp_f32_e32 v57, v48
	v_pk_mul_f32 v[48:49], v[52:53], s[28:29] op_sel_hi:[1,0]
	v_mul_f32_e32 v50, 0xbfb8aa3b, v50
	v_pk_mul_f32 v[52:53], v[248:249], v[48:49]
	v_exp_f32_e32 v50, v50
	v_pk_add_f32 v[60:61], v[52:53], v[52:53]
	v_mul_f32_e32 v48, 0x3fb8aa3b, v52
	v_fmamk_f32 v49, v60, 0x3ab60b61, v195
	v_exp_f32_e32 v48, v48
	v_fmaak_f32 v49, v60, v49, 0x3d2aaaab
	v_fmaak_f32 v49, v60, v49, 0x3e2aaaab
	v_exp_f32_e32 v54, v54
	v_fma_f32 v49, v60, v49, 0.5
	v_add_f32_e32 v50, 1.0, v50
	v_fma_f32 v49, v60, v49, 1.0
	v_rcp_f32_e32 v55, v50
	v_add_f32_e32 v50, v51, v247
	v_mul_f32_e64 v49, v49, -v60
	v_fma_f32 v52, -v48, v48, 1.0
	v_cmp_lt_f32_e64 s[6:7], s84, v60
	v_mul_f32_e32 v50, 0xbfb8aa3b, v50
	v_add_f32_e32 v54, 1.0, v54
	v_cndmask_b32_e64 v49, v52, v49, s[6:7]
	v_exp_f32_e32 v50, v50
	v_sqrt_f32_e32 v52, v49
	v_mul_f32_e32 v49, 0x3fb8aa3b, v53
	v_fmamk_f32 v53, v61, 0x3ab60b61, v195
	v_rcp_f32_e32 v54, v54
	v_exp_f32_e32 v49, v49
	v_fmaak_f32 v53, v61, v53, 0x3d2aaaab
	v_fmaak_f32 v53, v61, v53, 0x3e2aaaab
	v_fma_f32 v53, v61, v53, 0.5
	v_add_f32_e32 v50, 1.0, v50
	v_fma_f32 v53, v61, v53, 1.0
	v_rcp_f32_e32 v59, v50
	v_pk_mul_f32 v[50:51], v[54:55], s[28:29] op_sel_hi:[1,0]
	v_cmp_lt_f32_e32 vcc, s84, v61
	v_mul_f32_e64 v53, v53, -v61
	v_fma_f32 v60, -v49, v49, 1.0
	v_pk_mul_f32 v[54:55], v[250:251], v[50:51]
	v_cndmask_b32_e32 v53, v60, v53, vcc
	v_pk_add_f32 v[60:61], v[54:55], v[54:55]
	v_mul_f32_e32 v50, 0x3fb8aa3b, v54
	v_fmamk_f32 v51, v60, 0x3ab60b61, v195
	v_exp_f32_e32 v50, v50
	v_fmaak_f32 v51, v60, v51, 0x3d2aaaab
	v_fmaak_f32 v51, v60, v51, 0x3e2aaaab
	v_fma_f32 v51, v60, v51, 0.5
	v_fma_f32 v51, v60, v51, 1.0
	v_mul_f32_e64 v51, v51, -v60
	v_fma_f32 v54, -v50, v50, 1.0
	v_cmp_lt_f32_e64 s[6:7], s84, v60
	v_cmp_lt_f32_e32 vcc, s84, v61
	v_sqrt_f32_e32 v53, v53
	v_cndmask_b32_e64 v51, v54, v51, s[6:7]
	v_sqrt_f32_e32 v54, v51
	v_mul_f32_e32 v51, 0x3fb8aa3b, v55
	v_fmamk_f32 v55, v61, 0x3ab60b61, v195
	v_exp_f32_e32 v51, v51
	v_fmaak_f32 v55, v61, v55, 0x3d2aaaab
	v_fmaak_f32 v55, v61, v55, 0x3e2aaaab
	v_fma_f32 v55, v61, v55, 0.5
	v_fma_f32 v55, v61, v55, 1.0
	v_mul_f32_e64 v55, v55, -v61
	v_fma_f32 v60, -v51, v51, 1.0
	v_cndmask_b32_e32 v55, v60, v55, vcc
	v_sqrt_f32_e32 v55, v55
	v_pk_mul_f32 v[52:53], v[56:57], v[52:53]
	s_mov_b64 s[6:7], s[40:41]
	v_pk_mul_f32 v[52:53], v[52:53], v[74:75]
	v_pk_mul_f32 v[54:55], v[58:59], v[54:55]
	v_bitop3_b32 v60, v88, v86, 6 bitop3:0x36
	v_pk_mul_f32 v[54:55], v[54:55], v[72:73]
	ds_write_b128 v66, v[48:51] offset:8320
	ds_write_b128 v66, v[52:55] offset:24704
	v_lshlrev_b32_e32 v60, 4, v60
	v_lshl_add_u64 v[48:49], s[6:7], 0, v[64:65]
	s_mov_b64 s[6:7], s[44:45]
	v_add3_u32 v60, v89, v60, v87
	v_lshl_add_u64 v[52:53], s[6:7], 0, v[64:65]
	s_mov_b64 s[6:7], s[74:75]
	s_add_u32 s6, s6, s3
	s_addc_u32 s7, s7, 0
	v_lshl_add_u64 v[56:57], s[6:7], 0, v[144:145]
	v_add_co_u32_e32 v56, vcc, s27, v56
	ds_read_b64 v[60:61], v60
	s_nop 0
	v_addc_co_u32_e32 v57, vcc, 0, v57, vcc
	s_waitcnt lgkmcnt(0)
	v_lshlrev_b32_e32 v62, 16, v60
	v_and_b32_e32 v63, 0xffff0000, v60
	v_lshlrev_b32_e32 v60, 16, v61
	v_and_b32_e32 v61, 0xffff0000, v61
	s_waitcnt vmcnt(0)
	v_add_f32_e32 v12, v12, v180
	v_mul_f32_e32 v12, 0xbfb8aa3b, v12
	v_exp_f32_e32 v12, v12
	v_add_f32_e32 v14, v14, v182
	v_add_f32_e32 v8, v8, v146
	v_mul_f32_e32 v8, 0xbfb8aa3b, v8
	v_exp_f32_e32 v8, v8
	v_add_f32_e32 v10, v10, v148
	v_mul_f32_e32 v10, 0xbfb8aa3b, v10
	v_add_f32_e32 v12, 1.0, v12
	v_add_f32_e32 v8, 1.0, v8
	v_rcp_f32_e32 v48, v8
	v_add_f32_e32 v8, v13, v181
	v_mul_f32_e32 v8, 0xbfb8aa3b, v8
	v_exp_f32_e32 v8, v8
	v_exp_f32_e32 v10, v10
	v_rcp_f32_e32 v12, v12
	v_mul_f32_e32 v14, 0xbfb8aa3b, v14
	v_add_f32_e32 v8, 1.0, v8
	v_rcp_f32_e32 v13, v8
	v_add_f32_e32 v8, v9, v147
	v_mul_f32_e32 v8, 0xbfb8aa3b, v8
	v_exp_f32_e32 v8, v8
	v_add_f32_e32 v10, 1.0, v10
	v_rcp_f32_e32 v50, v10
	v_add_f32_e32 v10, v15, v183
	v_add_f32_e32 v8, 1.0, v8
	v_rcp_f32_e32 v49, v8
	v_pk_mul_f32 v[8:9], v[12:13], s[28:29] op_sel_hi:[1,0]
	v_mul_f32_e32 v10, 0xbfb8aa3b, v10
	v_pk_mul_f32 v[12:13], v[104:105], v[8:9]
	v_exp_f32_e32 v10, v10
	v_pk_add_f32 v[52:53], v[12:13], v[12:13]
	v_mul_f32_e32 v8, 0x3fb8aa3b, v12
	v_fmamk_f32 v9, v52, 0x3ab60b61, v195
	v_exp_f32_e32 v8, v8
	v_fmaak_f32 v9, v52, v9, 0x3d2aaaab
	v_fmaak_f32 v9, v52, v9, 0x3e2aaaab
	v_exp_f32_e32 v14, v14
	v_fma_f32 v9, v52, v9, 0.5
	v_add_f32_e32 v10, 1.0, v10
	v_fma_f32 v9, v52, v9, 1.0
	v_rcp_f32_e32 v15, v10
	v_add_f32_e32 v10, v11, v149
	v_mul_f32_e64 v9, v9, -v52
	v_fma_f32 v12, -v8, v8, 1.0
	v_cmp_lt_f32_e64 s[6:7], s84, v52
	v_mul_f32_e32 v10, 0xbfb8aa3b, v10
	v_add_f32_e32 v14, 1.0, v14
	v_cndmask_b32_e64 v9, v12, v9, s[6:7]
	v_exp_f32_e32 v10, v10
	v_sqrt_f32_e32 v12, v9
	v_mul_f32_e32 v9, 0x3fb8aa3b, v13
	v_fmamk_f32 v13, v53, 0x3ab60b61, v195
	v_rcp_f32_e32 v14, v14
	v_exp_f32_e32 v9, v9
	v_fmaak_f32 v13, v53, v13, 0x3d2aaaab
	v_fmaak_f32 v13, v53, v13, 0x3e2aaaab
	v_fma_f32 v13, v53, v13, 0.5
	v_add_f32_e32 v10, 1.0, v10
	v_fma_f32 v13, v53, v13, 1.0
	v_rcp_f32_e32 v51, v10
	v_pk_mul_f32 v[10:11], v[14:15], s[28:29] op_sel_hi:[1,0]
	v_cmp_lt_f32_e32 vcc, s84, v53
	v_mul_f32_e64 v13, v13, -v53
	v_fma_f32 v52, -v9, v9, 1.0
	v_pk_mul_f32 v[14:15], v[106:107], v[10:11]
	v_cndmask_b32_e32 v13, v52, v13, vcc
	v_pk_add_f32 v[52:53], v[14:15], v[14:15]
	v_mul_f32_e32 v10, 0x3fb8aa3b, v14
	v_fmamk_f32 v11, v52, 0x3ab60b61, v195
	v_exp_f32_e32 v10, v10
	v_fmaak_f32 v11, v52, v11, 0x3d2aaaab
	v_fmaak_f32 v11, v52, v11, 0x3e2aaaab
	v_fma_f32 v11, v52, v11, 0.5
	v_fma_f32 v11, v52, v11, 1.0
	v_mul_f32_e64 v11, v11, -v52
	v_fma_f32 v14, -v10, v10, 1.0
	v_cmp_lt_f32_e64 s[6:7], s84, v52
	v_cmp_lt_f32_e32 vcc, s84, v53
	v_sqrt_f32_e32 v13, v13
	v_cndmask_b32_e64 v11, v14, v11, s[6:7]
	v_sqrt_f32_e32 v14, v11
	v_mul_f32_e32 v11, 0x3fb8aa3b, v15
	v_fmamk_f32 v15, v53, 0x3ab60b61, v195
	v_exp_f32_e32 v11, v11
	v_fmaak_f32 v15, v53, v15, 0x3d2aaaab
	v_fmaak_f32 v15, v53, v15, 0x3e2aaaab
	v_fma_f32 v15, v53, v15, 0.5
	v_fma_f32 v15, v53, v15, 1.0
	v_mul_f32_e64 v15, v15, -v53
	v_fma_f32 v52, -v11, v11, 1.0
	v_cndmask_b32_e32 v15, v52, v15, vcc
	v_sqrt_f32_e32 v15, v15
	v_pk_mul_f32 v[12:13], v[48:49], v[12:13]
	v_cmp_gt_u32_e32 vcc, 64, v83
	v_pk_mul_f32 v[12:13], v[12:13], v[62:63]
	v_pk_mul_f32 v[14:15], v[50:51], v[14:15]
	s_nop 0
	v_pk_mul_f32 v[14:15], v[14:15], v[60:61]
	ds_write_b128 v66, v[8:11] offset:8384
	ds_write_b128 v66, v[12:15] offset:24768
	v_and_b32_e32 v8, 63, v85
	v_lshlrev_b32_e32 v9, 2, v8
	v_lshl_or_b32 v9, v84, 12, v9
	v_add_u32_e32 v9, s60, v9
	s_waitcnt lgkmcnt(0)
	s_barrier
	ds_read2st64_b32 v[10:11], v9 offset0:32 offset1:33
	ds_read2st64_b32 v[12:13], v9 offset0:96 offset1:97
	ds_read2st64_b32 v[14:15], v9 offset0:34 offset1:35
	ds_read2st64_b32 v[48:49], v9 offset0:98 offset1:99
	s_waitcnt lgkmcnt(2)
	v_fma_f32 v12, 0, v10, v12
	v_fmac_f32_e32 v13, v12, v11
	v_mul_f32_e32 v10, v10, v11
	s_waitcnt lgkmcnt(0)
	v_fma_f32 v11, v13, v14, v48
	ds_read2st64_b32 v[12:13], v9 offset0:36 offset1:37
	ds_read2st64_b32 v[50:51], v9 offset0:100 offset1:101
	v_fmac_f32_e32 v49, v11, v15
	v_mov_b32_e32 v58, v14
	v_mul_f32_e32 v14, v10, v14
	v_mul_f32_e32 v14, v14, v15
	s_waitcnt lgkmcnt(0)
	v_fma_f32 v11, v49, v12, v50
	ds_read2st64_b32 v[48:49], v9 offset0:38 offset1:39
	ds_read2st64_b32 v[52:53], v9 offset0:102 offset1:103
	v_fmac_f32_e32 v51, v11, v13
	s_waitcnt lgkmcnt(1)
	v_mov_b32_e32 v62, v48
	s_waitcnt lgkmcnt(0)
	v_fma_f32 v11, v51, v48, v52
	ds_read2st64_b32 v[50:51], v9 offset0:40 offset1:41
	ds_read2st64_b32 v[54:55], v9 offset0:104 offset1:105
	v_fmac_f32_e32 v53, v11, v49
	s_waitcnt lgkmcnt(1)
	v_mov_b32_e32 v59, v51
	s_waitcnt lgkmcnt(0)
	v_fmac_f32_e32 v54, v53, v50
	ds_read2st64_b32 v[52:53], v9 offset0:42 offset1:43
	ds_read2st64_b32 v[56:57], v9 offset0:106 offset1:107
	v_mov_b32_e32 v11, v54
	v_mov_b32_e32 v54, v15
	v_pk_fma_f32 v[10:11], v[10:11], v[58:59], v[54:55]
	v_mov_b32_e32 v58, v13
	v_mov_b32_e32 v15, v11
	v_mov_b32_e32 v10, v12
	s_waitcnt lgkmcnt(1)
	v_mov_b32_e32 v11, v52
	v_pk_mul_f32 v[54:55], v[14:15], v[10:11]
	v_mov_b32_e32 v12, v13
	s_waitcnt lgkmcnt(0)
	v_mov_b32_e32 v59, v56
	v_pk_mul_f32 v[12:13], v[54:55], v[12:13]
	v_pk_fma_f32 v[10:11], v[14:15], v[10:11], v[58:59]
	ds_read2st64_b32 v[14:15], v9 offset0:44 offset1:45
	ds_read2st64_b32 v[54:55], v9 offset0:108 offset1:109
	ds_read2st64_b32 v[58:59], v9 offset0:46 offset1:47
	ds_read2st64_b32 v[60:61], v9 offset0:110 offset1:111
	v_and_b32_e32 v56, 0x1fffffc0, v83
	v_lshl_add_u32 v9, v8, 3, s60
	v_mov_b32_e32 v10, v12
	v_lshl_add_u32 v64, v56, 3, v9
	v_mov_b32_e32 v63, v53
	v_pk_mul_f32 v[12:13], v[12:13], v[48:49]
	v_mov_b32_e32 v48, v49
	v_mov_b32_e32 v56, v49
	v_pk_mul_f32 v[12:13], v[12:13], v[48:49]
	v_pk_fma_f32 v[10:11], v[10:11], v[62:63], v[56:57]
	v_mov_b32_e32 v56, v51
	v_mov_b32_e32 v13, v11
	v_mov_b32_e32 v10, v50
	s_waitcnt lgkmcnt(3)
	v_mov_b32_e32 v11, v14
	v_pk_mul_f32 v[48:49], v[12:13], v[10:11]
	v_mov_b32_e32 v50, v51
	s_waitcnt lgkmcnt(2)
	v_mov_b32_e32 v57, v54
	v_pk_mul_f32 v[48:49], v[48:49], v[50:51]
	v_pk_fma_f32 v[10:11], v[12:13], v[10:11], v[56:57]
	v_mov_b32_e32 v12, v52
	v_mov_b32_e32 v10, v48
	v_mov_b32_e32 v13, v15
	v_pk_mul_f32 v[48:49], v[48:49], v[52:53]
	v_mov_b32_e32 v50, v53
	v_mov_b32_e32 v54, v53
	v_pk_mul_f32 v[48:49], v[48:49], v[50:51]
	v_pk_fma_f32 v[10:11], v[10:11], v[12:13], v[54:55]
	v_mov_b32_e32 v50, v15
	v_mov_b32_e32 v49, v11
	v_mov_b32_e32 v10, v14
	s_waitcnt lgkmcnt(1)
	v_mov_b32_e32 v11, v58
	v_pk_mul_f32 v[12:13], v[48:49], v[10:11]
	v_mov_b32_e32 v14, v15
	s_waitcnt lgkmcnt(0)
	v_mov_b32_e32 v51, v60
	v_pk_mul_f32 v[12:13], v[12:13], v[14:15]
	v_pk_fma_f32 v[10:11], v[48:49], v[10:11], v[50:51]
	v_mov_b32_e32 v14, v59
	v_mov_b32_e32 v10, v12
	v_pk_mul_f32 v[12:13], v[12:13], v[58:59]
	v_mov_b32_e32 v60, v59
	v_pk_mul_f32 v[12:13], v[12:13], v[14:15]
	v_pk_fma_f32 v[10:11], v[10:11], v[58:59], v[60:61]
	s_nop 0
	v_mov_b32_e32 v13, v11
	ds_write_b64 v64, v[12:13] offset:40960
	s_waitcnt lgkmcnt(0)
	s_barrier
	s_and_saveexec_b64 s[6:7], vcc
	s_xor_b64 s[6:7], exec, s[6:7]
	s_cbranch_execz .LBB0_401
	s_lshl_b32 s27, s26, 7
	ds_read2st64_b64 v[10:13], v9 offset0:80 offset1:81
	ds_read2st64_b64 v[48:51], v9 offset0:82 offset1:83
	s_or_b32 s28, s27, s25
	s_ashr_i32 s29, s28, 31
	s_lshl_b64 s[28:29], s[28:29], 12
	s_mov_b64 s[30:31], s[74:75]
	s_add_u32 s27, s30, s28
	s_waitcnt lgkmcnt(1)
	v_fma_f32 v9, 0, v10, v11
	s_addc_u32 s29, s31, s29
	s_lshl_b32 s28, s23, 3
	v_fmac_f32_e32 v13, v9, v12
	s_add_u32 s28, s27, s28
	v_mul_f32_e32 v10, v10, v12
	s_waitcnt lgkmcnt(0)
	v_fma_f32 v11, v13, v48, v49
	v_mov_b32_e32 v49, v50
	s_addc_u32 s29, s29, 0
	v_lshlrev_b32_e32 v144, 3, v8
	v_pk_mul_f32 v[12:13], v[10:11], v[48:49]
	v_lshl_add_u64 v[8:9], s[28:29], 0, v[144:145]
	v_pk_mul_f32 v[12:13], v[12:13], v[50:51]
	v_pk_fma_f32 v[10:11], v[10:11], v[48:49], v[50:51]
	v_add_co_u32_e32 v8, vcc, 0x115e0000, v8
	v_mov_b32_e32 v13, v11
	s_nop 0
	v_addc_co_u32_e32 v9, vcc, 0, v9, vcc
	flat_store_dwordx2 v[8:9], v[12:13]
